# SwiGLU epilogue: paired f32 fma/mul/add into v_pk_*_f32 (bit-identical), -24 VALU per group
# speedup vs baseline: 1.0103x; 1.0103x over previous
.LBB0_255:
	v_mov_b32_e32 v178, 0xbfb8aa3b
	v_mov_b32_e32 v179, 0xbfb8aa3b
	s_lshl_b32 s11, s18, 8
	s_mov_b64 s[18:19], -1
	ds_read_b32 v182, v170
	ds_read_b32 v183, v170 offset:64
	ds_read_b32 v184, v170 offset:128
	ds_read_b32 v185, v170 offset:192
	ds_read_b32 v186, v170 offset:512
	ds_read_b32 v187, v170 offset:576
	ds_read_b32 v188, v170 offset:640
	ds_read_b32 v189, v170 offset:704
	v_add_u32_e32 v203, s11, v166
	v_lshl_or_b32 v202, s60, 7, v171
	v_lshlrev_b32_e32 v202, 1, v202
	v_mad_u32_u24 v202, v203, s86, v202
	s_waitcnt lgkmcnt(0)
	v_pk_fma_f32 v[132:133], v[132:133], v[182:183], v[238:239] op_sel_hi:[1,0,1]
	v_pk_fma_f32 v[134:135], v[134:135], v[182:183], v[240:241] op_sel_hi:[1,0,1]
	v_pk_fma_f32 v[124:125], v[124:125], v[182:183], v[242:243] op_sel_hi:[1,0,1]
	v_pk_fma_f32 v[126:127], v[126:127], v[182:183], v[244:245] op_sel_hi:[1,0,1]
	v_pk_fma_f32 v[128:129], v[128:129], v[182:183], v[246:247] op_sel_hi:[1,0,1]
	v_pk_fma_f32 v[130:131], v[130:131], v[182:183], v[248:249] op_sel_hi:[1,0,1]
	v_pk_fma_f32 v[120:121], v[120:121], v[182:183], v[250:251] op_sel_hi:[1,0,1]
	v_pk_fma_f32 v[122:123], v[122:123], v[182:183], v[252:253] op_sel_hi:[1,0,1]
	v_pk_mul_f32 v[190:191], v[132:133], v[178:179]
	v_pk_mul_f32 v[192:193], v[134:135], v[178:179]
	v_pk_mul_f32 v[194:195], v[124:125], v[178:179]
	v_pk_mul_f32 v[196:197], v[126:127], v[178:179]
	v_exp_f32_e32 v190, v190
	v_exp_f32_e32 v191, v191
	v_exp_f32_e32 v192, v192
	v_exp_f32_e32 v193, v193
	v_exp_f32_e32 v194, v194
	v_exp_f32_e32 v195, v195
	v_exp_f32_e32 v196, v196
	v_exp_f32_e32 v197, v197
	v_pk_add_f32 v[190:191], v[190:191], 1.0 op_sel_hi:[1,0]
	v_pk_add_f32 v[192:193], v[192:193], 1.0 op_sel_hi:[1,0]
	v_pk_add_f32 v[194:195], v[194:195], 1.0 op_sel_hi:[1,0]
	v_pk_add_f32 v[196:197], v[196:197], 1.0 op_sel_hi:[1,0]
	v_rcp_f32_e32 v190, v190
	v_rcp_f32_e32 v191, v191
	v_rcp_f32_e32 v192, v192
	v_rcp_f32_e32 v193, v193
	v_rcp_f32_e32 v194, v194
	v_rcp_f32_e32 v195, v195
	v_rcp_f32_e32 v196, v196
	v_rcp_f32_e32 v197, v197
	v_pk_mul_f32 v[132:133], v[132:133], v[190:191]
	v_pk_mul_f32 v[134:135], v[134:135], v[192:193]
	v_pk_mul_f32 v[124:125], v[124:125], v[194:195]
	v_pk_mul_f32 v[126:127], v[126:127], v[196:197]
	v_pk_mul_f32 v[132:133], v[132:133], v[128:129]
	v_pk_mul_f32 v[134:135], v[134:135], v[130:131]
	v_pk_mul_f32 v[124:125], v[124:125], v[120:121]
	v_pk_mul_f32 v[126:127], v[126:127], v[122:123]
	v_cvt_pk_bf16_f32 v198, v132, v133
	v_cvt_pk_bf16_f32 v199, v134, v135
	v_cvt_pk_bf16_f32 v200, v124, v125
	v_cvt_pk_bf16_f32 v201, v126, v127
	global_store_dwordx4 v202, v[198:201], s[6:7]
	v_pk_fma_f32 v[116:117], v[116:117], v[182:183], v[238:239] op_sel:[0,1,0] op_sel_hi:[1,1,1]
	v_pk_fma_f32 v[118:119], v[118:119], v[182:183], v[240:241] op_sel:[0,1,0] op_sel_hi:[1,1,1]
	v_pk_fma_f32 v[112:113], v[112:113], v[182:183], v[242:243] op_sel:[0,1,0] op_sel_hi:[1,1,1]
	v_pk_fma_f32 v[114:115], v[114:115], v[182:183], v[244:245] op_sel:[0,1,0] op_sel_hi:[1,1,1]
	v_pk_fma_f32 v[108:109], v[108:109], v[182:183], v[246:247] op_sel:[0,1,0] op_sel_hi:[1,1,1]
	v_pk_fma_f32 v[110:111], v[110:111], v[182:183], v[248:249] op_sel:[0,1,0] op_sel_hi:[1,1,1]
	v_pk_fma_f32 v[104:105], v[104:105], v[182:183], v[250:251] op_sel:[0,1,0] op_sel_hi:[1,1,1]
	v_pk_fma_f32 v[106:107], v[106:107], v[182:183], v[252:253] op_sel:[0,1,0] op_sel_hi:[1,1,1]
	v_pk_mul_f32 v[190:191], v[116:117], v[178:179]
	v_pk_mul_f32 v[192:193], v[118:119], v[178:179]
	v_pk_mul_f32 v[194:195], v[112:113], v[178:179]
	v_pk_mul_f32 v[196:197], v[114:115], v[178:179]
	v_exp_f32_e32 v190, v190
	v_exp_f32_e32 v191, v191
	v_exp_f32_e32 v192, v192
	v_exp_f32_e32 v193, v193
	v_exp_f32_e32 v194, v194
	v_exp_f32_e32 v195, v195
	v_exp_f32_e32 v196, v196
	v_exp_f32_e32 v197, v197
	v_pk_add_f32 v[190:191], v[190:191], 1.0 op_sel_hi:[1,0]
	v_pk_add_f32 v[192:193], v[192:193], 1.0 op_sel_hi:[1,0]
	v_pk_add_f32 v[194:195], v[194:195], 1.0 op_sel_hi:[1,0]
	v_pk_add_f32 v[196:197], v[196:197], 1.0 op_sel_hi:[1,0]
	v_rcp_f32_e32 v190, v190
	v_rcp_f32_e32 v191, v191
	v_rcp_f32_e32 v192, v192
	v_rcp_f32_e32 v193, v193
	v_rcp_f32_e32 v194, v194
	v_rcp_f32_e32 v195, v195
	v_rcp_f32_e32 v196, v196
	v_rcp_f32_e32 v197, v197
	v_pk_mul_f32 v[116:117], v[116:117], v[190:191]
	v_pk_mul_f32 v[118:119], v[118:119], v[192:193]
	v_pk_mul_f32 v[112:113], v[112:113], v[194:195]
	v_pk_mul_f32 v[114:115], v[114:115], v[196:197]
	v_pk_mul_f32 v[116:117], v[116:117], v[108:109]
	v_pk_mul_f32 v[118:119], v[118:119], v[110:111]
	v_pk_mul_f32 v[112:113], v[112:113], v[104:105]
	v_pk_mul_f32 v[114:115], v[114:115], v[106:107]
	v_cvt_pk_bf16_f32 v198, v116, v117
	v_cvt_pk_bf16_f32 v199, v118, v119
	v_cvt_pk_bf16_f32 v200, v112, v113
	v_cvt_pk_bf16_f32 v201, v114, v115
	v_add_u32_e32 v203, 0x16000, v202
	s_nop 0
	global_store_dwordx4 v203, v[198:201], s[6:7]
	v_pk_fma_f32 v[100:101], v[100:101], v[184:185], v[238:239] op_sel_hi:[1,0,1]
	v_pk_fma_f32 v[102:103], v[102:103], v[184:185], v[240:241] op_sel_hi:[1,0,1]
	v_pk_fma_f32 v[96:97], v[96:97], v[184:185], v[242:243] op_sel_hi:[1,0,1]
	v_pk_fma_f32 v[98:99], v[98:99], v[184:185], v[244:245] op_sel_hi:[1,0,1]
	v_pk_fma_f32 v[92:93], v[92:93], v[184:185], v[246:247] op_sel_hi:[1,0,1]
	v_pk_fma_f32 v[94:95], v[94:95], v[184:185], v[248:249] op_sel_hi:[1,0,1]
	v_pk_fma_f32 v[88:89], v[88:89], v[184:185], v[250:251] op_sel_hi:[1,0,1]
	v_pk_fma_f32 v[90:91], v[90:91], v[184:185], v[252:253] op_sel_hi:[1,0,1]
	v_pk_mul_f32 v[190:191], v[100:101], v[178:179]
	v_pk_mul_f32 v[192:193], v[102:103], v[178:179]
	v_pk_mul_f32 v[194:195], v[96:97], v[178:179]
	v_pk_mul_f32 v[196:197], v[98:99], v[178:179]
	v_exp_f32_e32 v190, v190
	v_exp_f32_e32 v191, v191
	v_exp_f32_e32 v192, v192
	v_exp_f32_e32 v193, v193
	v_exp_f32_e32 v194, v194
	v_exp_f32_e32 v195, v195
	v_exp_f32_e32 v196, v196
	v_exp_f32_e32 v197, v197
	v_pk_add_f32 v[190:191], v[190:191], 1.0 op_sel_hi:[1,0]
	v_pk_add_f32 v[192:193], v[192:193], 1.0 op_sel_hi:[1,0]
	v_pk_add_f32 v[194:195], v[194:195], 1.0 op_sel_hi:[1,0]
	v_pk_add_f32 v[196:197], v[196:197], 1.0 op_sel_hi:[1,0]
	v_rcp_f32_e32 v190, v190
	v_rcp_f32_e32 v191, v191
	v_rcp_f32_e32 v192, v192
	v_rcp_f32_e32 v193, v193
	v_rcp_f32_e32 v194, v194
	v_rcp_f32_e32 v195, v195
	v_rcp_f32_e32 v196, v196
	v_rcp_f32_e32 v197, v197
	v_pk_mul_f32 v[100:101], v[100:101], v[190:191]
	v_pk_mul_f32 v[102:103], v[102:103], v[192:193]
	v_pk_mul_f32 v[96:97], v[96:97], v[194:195]
	v_pk_mul_f32 v[98:99], v[98:99], v[196:197]
	v_pk_mul_f32 v[100:101], v[100:101], v[92:93]
	v_pk_mul_f32 v[102:103], v[102:103], v[94:95]
	v_pk_mul_f32 v[96:97], v[96:97], v[88:89]
	v_pk_mul_f32 v[98:99], v[98:99], v[90:91]
	v_cvt_pk_bf16_f32 v198, v100, v101
	v_cvt_pk_bf16_f32 v199, v102, v103
	v_cvt_pk_bf16_f32 v200, v96, v97
	v_cvt_pk_bf16_f32 v201, v98, v99
	v_add_u32_e32 v203, 0x2c000, v202
	s_nop 0
	global_store_dwordx4 v203, v[198:201], s[6:7]
	v_pk_fma_f32 v[84:85], v[84:85], v[184:185], v[238:239] op_sel:[0,1,0] op_sel_hi:[1,1,1]
	v_pk_fma_f32 v[86:87], v[86:87], v[184:185], v[240:241] op_sel:[0,1,0] op_sel_hi:[1,1,1]
	v_pk_fma_f32 v[80:81], v[80:81], v[184:185], v[242:243] op_sel:[0,1,0] op_sel_hi:[1,1,1]
	v_pk_fma_f32 v[82:83], v[82:83], v[184:185], v[244:245] op_sel:[0,1,0] op_sel_hi:[1,1,1]
	v_pk_fma_f32 v[76:77], v[76:77], v[184:185], v[246:247] op_sel:[0,1,0] op_sel_hi:[1,1,1]
	v_pk_fma_f32 v[78:79], v[78:79], v[184:185], v[248:249] op_sel:[0,1,0] op_sel_hi:[1,1,1]
	v_pk_fma_f32 v[72:73], v[72:73], v[184:185], v[250:251] op_sel:[0,1,0] op_sel_hi:[1,1,1]
	v_pk_fma_f32 v[74:75], v[74:75], v[184:185], v[252:253] op_sel:[0,1,0] op_sel_hi:[1,1,1]
	v_pk_mul_f32 v[190:191], v[84:85], v[178:179]
	v_pk_mul_f32 v[192:193], v[86:87], v[178:179]
	v_pk_mul_f32 v[194:195], v[80:81], v[178:179]
	v_pk_mul_f32 v[196:197], v[82:83], v[178:179]
	v_exp_f32_e32 v190, v190
	v_exp_f32_e32 v191, v191
	v_exp_f32_e32 v192, v192
	v_exp_f32_e32 v193, v193
	v_exp_f32_e32 v194, v194
	v_exp_f32_e32 v195, v195
	v_exp_f32_e32 v196, v196
	v_exp_f32_e32 v197, v197
	v_pk_add_f32 v[190:191], v[190:191], 1.0 op_sel_hi:[1,0]
	v_pk_add_f32 v[192:193], v[192:193], 1.0 op_sel_hi:[1,0]
	v_pk_add_f32 v[194:195], v[194:195], 1.0 op_sel_hi:[1,0]
	v_pk_add_f32 v[196:197], v[196:197], 1.0 op_sel_hi:[1,0]
	v_rcp_f32_e32 v190, v190
	v_rcp_f32_e32 v191, v191
	v_rcp_f32_e32 v192, v192
	v_rcp_f32_e32 v193, v193
	v_rcp_f32_e32 v194, v194
	v_rcp_f32_e32 v195, v195
	v_rcp_f32_e32 v196, v196
	v_rcp_f32_e32 v197, v197
	v_pk_mul_f32 v[84:85], v[84:85], v[190:191]
	v_pk_mul_f32 v[86:87], v[86:87], v[192:193]
	v_pk_mul_f32 v[80:81], v[80:81], v[194:195]
	v_pk_mul_f32 v[82:83], v[82:83], v[196:197]
	v_pk_mul_f32 v[84:85], v[84:85], v[76:77]
	v_pk_mul_f32 v[86:87], v[86:87], v[78:79]
	v_pk_mul_f32 v[80:81], v[80:81], v[72:73]
	v_pk_mul_f32 v[82:83], v[82:83], v[74:75]
	v_cvt_pk_bf16_f32 v198, v84, v85
	v_cvt_pk_bf16_f32 v199, v86, v87
	v_cvt_pk_bf16_f32 v200, v80, v81
	v_cvt_pk_bf16_f32 v201, v82, v83
	v_add_u32_e32 v203, 0x42000, v202
	s_nop 0
	global_store_dwordx4 v203, v[198:201], s[6:7]
	v_pk_fma_f32 v[68:69], v[68:69], v[186:187], v[238:239] op_sel_hi:[1,0,1]
	v_pk_fma_f32 v[70:71], v[70:71], v[186:187], v[240:241] op_sel_hi:[1,0,1]
	v_pk_fma_f32 v[64:65], v[64:65], v[186:187], v[242:243] op_sel_hi:[1,0,1]
	v_pk_fma_f32 v[66:67], v[66:67], v[186:187], v[244:245] op_sel_hi:[1,0,1]
	v_pk_fma_f32 v[60:61], v[60:61], v[186:187], v[246:247] op_sel_hi:[1,0,1]
	v_pk_fma_f32 v[62:63], v[62:63], v[186:187], v[248:249] op_sel_hi:[1,0,1]
	v_pk_fma_f32 v[52:53], v[52:53], v[186:187], v[250:251] op_sel_hi:[1,0,1]
	v_pk_fma_f32 v[54:55], v[54:55], v[186:187], v[252:253] op_sel_hi:[1,0,1]
	v_pk_mul_f32 v[190:191], v[68:69], v[178:179]
	v_pk_mul_f32 v[192:193], v[70:71], v[178:179]
	v_pk_mul_f32 v[194:195], v[64:65], v[178:179]
	v_pk_mul_f32 v[196:197], v[66:67], v[178:179]
	v_exp_f32_e32 v190, v190
	v_exp_f32_e32 v191, v191
	v_exp_f32_e32 v192, v192
	v_exp_f32_e32 v193, v193
	v_exp_f32_e32 v194, v194
	v_exp_f32_e32 v195, v195
	v_exp_f32_e32 v196, v196
	v_exp_f32_e32 v197, v197
	v_pk_add_f32 v[190:191], v[190:191], 1.0 op_sel_hi:[1,0]
	v_pk_add_f32 v[192:193], v[192:193], 1.0 op_sel_hi:[1,0]
	v_pk_add_f32 v[194:195], v[194:195], 1.0 op_sel_hi:[1,0]
	v_pk_add_f32 v[196:197], v[196:197], 1.0 op_sel_hi:[1,0]
	v_rcp_f32_e32 v190, v190
	v_rcp_f32_e32 v191, v191
	v_rcp_f32_e32 v192, v192
	v_rcp_f32_e32 v193, v193
	v_rcp_f32_e32 v194, v194
	v_rcp_f32_e32 v195, v195
	v_rcp_f32_e32 v196, v196
	v_rcp_f32_e32 v197, v197
	v_pk_mul_f32 v[68:69], v[68:69], v[190:191]
	v_pk_mul_f32 v[70:71], v[70:71], v[192:193]
	v_pk_mul_f32 v[64:65], v[64:65], v[194:195]
	v_pk_mul_f32 v[66:67], v[66:67], v[196:197]
	v_pk_mul_f32 v[68:69], v[68:69], v[60:61]
	v_pk_mul_f32 v[70:71], v[70:71], v[62:63]
	v_pk_mul_f32 v[64:65], v[64:65], v[52:53]
	v_pk_mul_f32 v[66:67], v[66:67], v[54:55]
	v_cvt_pk_bf16_f32 v198, v68, v69
	v_cvt_pk_bf16_f32 v199, v70, v71
	v_cvt_pk_bf16_f32 v200, v64, v65
	v_cvt_pk_bf16_f32 v201, v66, v67
	v_add_u32_e32 v203, 0xb0000, v202
	s_nop 0
	global_store_dwordx4 v203, v[198:201], s[6:7]
	v_pk_fma_f32 v[44:45], v[44:45], v[186:187], v[238:239] op_sel:[0,1,0] op_sel_hi:[1,1,1]
	v_pk_fma_f32 v[46:47], v[46:47], v[186:187], v[240:241] op_sel:[0,1,0] op_sel_hi:[1,1,1]
	v_pk_fma_f32 v[40:41], v[40:41], v[186:187], v[242:243] op_sel:[0,1,0] op_sel_hi:[1,1,1]
	v_pk_fma_f32 v[42:43], v[42:43], v[186:187], v[244:245] op_sel:[0,1,0] op_sel_hi:[1,1,1]
	v_pk_fma_f32 v[36:37], v[36:37], v[186:187], v[246:247] op_sel:[0,1,0] op_sel_hi:[1,1,1]
	v_pk_fma_f32 v[38:39], v[38:39], v[186:187], v[248:249] op_sel:[0,1,0] op_sel_hi:[1,1,1]
	v_pk_fma_f32 v[32:33], v[32:33], v[186:187], v[250:251] op_sel:[0,1,0] op_sel_hi:[1,1,1]
	v_pk_fma_f32 v[34:35], v[34:35], v[186:187], v[252:253] op_sel:[0,1,0] op_sel_hi:[1,1,1]
	v_pk_mul_f32 v[190:191], v[44:45], v[178:179]
	v_pk_mul_f32 v[192:193], v[46:47], v[178:179]
	v_pk_mul_f32 v[194:195], v[40:41], v[178:179]
	v_pk_mul_f32 v[196:197], v[42:43], v[178:179]
	v_exp_f32_e32 v190, v190
	v_exp_f32_e32 v191, v191
	v_exp_f32_e32 v192, v192
	v_exp_f32_e32 v193, v193
	v_exp_f32_e32 v194, v194
	v_exp_f32_e32 v195, v195
	v_exp_f32_e32 v196, v196
	v_exp_f32_e32 v197, v197
	v_pk_add_f32 v[190:191], v[190:191], 1.0 op_sel_hi:[1,0]
	v_pk_add_f32 v[192:193], v[192:193], 1.0 op_sel_hi:[1,0]
	v_pk_add_f32 v[194:195], v[194:195], 1.0 op_sel_hi:[1,0]
	v_pk_add_f32 v[196:197], v[196:197], 1.0 op_sel_hi:[1,0]
	v_rcp_f32_e32 v190, v190
	v_rcp_f32_e32 v191, v191
	v_rcp_f32_e32 v192, v192
	v_rcp_f32_e32 v193, v193
	v_rcp_f32_e32 v194, v194
	v_rcp_f32_e32 v195, v195
	v_rcp_f32_e32 v196, v196
	v_rcp_f32_e32 v197, v197
	v_pk_mul_f32 v[44:45], v[44:45], v[190:191]
	v_pk_mul_f32 v[46:47], v[46:47], v[192:193]
	v_pk_mul_f32 v[40:41], v[40:41], v[194:195]
	v_pk_mul_f32 v[42:43], v[42:43], v[196:197]
	v_pk_mul_f32 v[44:45], v[44:45], v[36:37]
	v_pk_mul_f32 v[46:47], v[46:47], v[38:39]
	v_pk_mul_f32 v[40:41], v[40:41], v[32:33]
	v_pk_mul_f32 v[42:43], v[42:43], v[34:35]
	v_cvt_pk_bf16_f32 v198, v44, v45
	v_cvt_pk_bf16_f32 v199, v46, v47
	v_cvt_pk_bf16_f32 v200, v40, v41
	v_cvt_pk_bf16_f32 v201, v42, v43
	v_add_u32_e32 v203, 0xc6000, v202
	s_nop 0
	global_store_dwordx4 v203, v[198:201], s[6:7]
	v_pk_fma_f32 v[28:29], v[28:29], v[188:189], v[238:239] op_sel_hi:[1,0,1]
	v_pk_fma_f32 v[30:31], v[30:31], v[188:189], v[240:241] op_sel_hi:[1,0,1]
	v_pk_fma_f32 v[24:25], v[24:25], v[188:189], v[242:243] op_sel_hi:[1,0,1]
	v_pk_fma_f32 v[26:27], v[26:27], v[188:189], v[244:245] op_sel_hi:[1,0,1]
	v_pk_fma_f32 v[20:21], v[20:21], v[188:189], v[246:247] op_sel_hi:[1,0,1]
	v_pk_fma_f32 v[22:23], v[22:23], v[188:189], v[248:249] op_sel_hi:[1,0,1]
	v_pk_fma_f32 v[16:17], v[16:17], v[188:189], v[250:251] op_sel_hi:[1,0,1]
	v_pk_fma_f32 v[18:19], v[18:19], v[188:189], v[252:253] op_sel_hi:[1,0,1]
	v_pk_mul_f32 v[190:191], v[28:29], v[178:179]
	v_pk_mul_f32 v[192:193], v[30:31], v[178:179]
	v_pk_mul_f32 v[194:195], v[24:25], v[178:179]
	v_pk_mul_f32 v[196:197], v[26:27], v[178:179]
	v_exp_f32_e32 v190, v190
	v_exp_f32_e32 v191, v191
	v_exp_f32_e32 v192, v192
	v_exp_f32_e32 v193, v193
	v_exp_f32_e32 v194, v194
	v_exp_f32_e32 v195, v195
	v_exp_f32_e32 v196, v196
	v_exp_f32_e32 v197, v197
	v_pk_add_f32 v[190:191], v[190:191], 1.0 op_sel_hi:[1,0]
	v_pk_add_f32 v[192:193], v[192:193], 1.0 op_sel_hi:[1,0]
	v_pk_add_f32 v[194:195], v[194:195], 1.0 op_sel_hi:[1,0]
	v_pk_add_f32 v[196:197], v[196:197], 1.0 op_sel_hi:[1,0]
	v_rcp_f32_e32 v190, v190
	v_rcp_f32_e32 v191, v191
	v_rcp_f32_e32 v192, v192
	v_rcp_f32_e32 v193, v193
	v_rcp_f32_e32 v194, v194
	v_rcp_f32_e32 v195, v195
	v_rcp_f32_e32 v196, v196
	v_rcp_f32_e32 v197, v197
	v_pk_mul_f32 v[28:29], v[28:29], v[190:191]
	v_pk_mul_f32 v[30:31], v[30:31], v[192:193]
	v_pk_mul_f32 v[24:25], v[24:25], v[194:195]
	v_pk_mul_f32 v[26:27], v[26:27], v[196:197]
	v_pk_mul_f32 v[28:29], v[28:29], v[20:21]
	v_pk_mul_f32 v[30:31], v[30:31], v[22:23]
	v_pk_mul_f32 v[24:25], v[24:25], v[16:17]
	v_pk_mul_f32 v[26:27], v[26:27], v[18:19]
	v_cvt_pk_bf16_f32 v198, v28, v29
	v_cvt_pk_bf16_f32 v199, v30, v31
	v_cvt_pk_bf16_f32 v200, v24, v25
	v_cvt_pk_bf16_f32 v201, v26, v27
	v_add_u32_e32 v203, 0xdc000, v202
	s_nop 0
	global_store_dwordx4 v203, v[198:201], s[6:7]
	v_pk_fma_f32 v[12:13], v[12:13], v[188:189], v[238:239] op_sel:[0,1,0] op_sel_hi:[1,1,1]
	v_pk_fma_f32 v[14:15], v[14:15], v[188:189], v[240:241] op_sel:[0,1,0] op_sel_hi:[1,1,1]
	v_pk_fma_f32 v[8:9], v[8:9], v[188:189], v[242:243] op_sel:[0,1,0] op_sel_hi:[1,1,1]
	v_pk_fma_f32 v[10:11], v[10:11], v[188:189], v[244:245] op_sel:[0,1,0] op_sel_hi:[1,1,1]
	v_pk_fma_f32 v[4:5], v[4:5], v[188:189], v[246:247] op_sel:[0,1,0] op_sel_hi:[1,1,1]
	v_pk_fma_f32 v[6:7], v[6:7], v[188:189], v[248:249] op_sel:[0,1,0] op_sel_hi:[1,1,1]
	v_pk_fma_f32 v[0:1], v[0:1], v[188:189], v[250:251] op_sel:[0,1,0] op_sel_hi:[1,1,1]
	v_pk_fma_f32 v[2:3], v[2:3], v[188:189], v[252:253] op_sel:[0,1,0] op_sel_hi:[1,1,1]
	v_pk_mul_f32 v[190:191], v[12:13], v[178:179]
	v_pk_mul_f32 v[192:193], v[14:15], v[178:179]
	v_pk_mul_f32 v[194:195], v[8:9], v[178:179]
	v_pk_mul_f32 v[196:197], v[10:11], v[178:179]
	v_exp_f32_e32 v190, v190
	v_exp_f32_e32 v191, v191
	v_exp_f32_e32 v192, v192
	v_exp_f32_e32 v193, v193
	v_exp_f32_e32 v194, v194
	v_exp_f32_e32 v195, v195
	v_exp_f32_e32 v196, v196
	v_exp_f32_e32 v197, v197
	v_pk_add_f32 v[190:191], v[190:191], 1.0 op_sel_hi:[1,0]
	v_pk_add_f32 v[192:193], v[192:193], 1.0 op_sel_hi:[1,0]
	v_pk_add_f32 v[194:195], v[194:195], 1.0 op_sel_hi:[1,0]
	v_pk_add_f32 v[196:197], v[196:197], 1.0 op_sel_hi:[1,0]
	v_rcp_f32_e32 v190, v190
	v_rcp_f32_e32 v191, v191
	v_rcp_f32_e32 v192, v192
	v_rcp_f32_e32 v193, v193
	v_rcp_f32_e32 v194, v194
	v_rcp_f32_e32 v195, v195
	v_rcp_f32_e32 v196, v196
	v_rcp_f32_e32 v197, v197
	v_pk_mul_f32 v[12:13], v[12:13], v[190:191]
	v_pk_mul_f32 v[14:15], v[14:15], v[192:193]
	v_pk_mul_f32 v[8:9], v[8:9], v[194:195]
	v_pk_mul_f32 v[10:11], v[10:11], v[196:197]
	v_pk_mul_f32 v[12:13], v[12:13], v[4:5]
	v_pk_mul_f32 v[14:15], v[14:15], v[6:7]
	v_pk_mul_f32 v[8:9], v[8:9], v[0:1]
	v_pk_mul_f32 v[10:11], v[10:11], v[2:3]
	v_cvt_pk_bf16_f32 v198, v12, v13
	v_cvt_pk_bf16_f32 v199, v14, v15
	v_cvt_pk_bf16_f32 v200, v8, v9
	v_cvt_pk_bf16_f32 v201, v10, v11
	v_add_u32_e32 v203, 0xf2000, v202
	s_nop 0
	global_store_dwordx4 v203, v[198:201], s[6:7]
	s_andn2_b64 vcc, exec, s[4:5]
	s_cbranch_vccnz .LBB0_248
	s_andn2_b64 vcc, exec, s[0:1]
	s_cbranch_vccnz .LBB0_247
	s_barrier
	s_branch .LBB0_247
